# v043 with in-proj GEMM start-stagger unit 0x50 instead of 0x64 (tile time shrank after MALL-resident A)
# baseline (speedup 1.0000x reference)
.LBB0_119:
	s_add_i32 s0, s0, -1
	s_cmp_lg_u32 s0, 0
	s_sleep 0x50
	s_cbranch_scc1 .LBB0_119
